# proj-GEMM QK-norm epilogue: ds_bpermute lane reductions replaced by v_permlane16/32_swap (bit-identical), added to FFN1 epilogue permlane reductions + DF-loop LDS pipelining + prep loop pipelining
# baseline (speedup 1.0000x reference)
; #define PG8_GATHER(ai, m) float a[8], b[8]; _Pragma("unroll") for (int j = 0; j < 4; ++j) { a[j] = acc[ai][0][m][0][j]; a[4 + j] = acc[ai][0][m][1][j]; b[j] = acc[ai][1][m][0][j]; b[4 + j] = acc[ai][1][m][1][j]; }
; __device__ __forceinline__ void run_epi_qknorm(const EpiProj& E, const f32x4 (&acc)[2][2][4][2], const Unit& u, int wr, int wc, int fr, int fq, LAS unsigned char* lds) {
;     if (u.pn < 12 || u.pn >= 20) { run_epi(E, acc, u, wr, wc, fr, fq); return; }
;     ...
;         for (int m = 0; m < 4; ++m) { const int rl = ai * HALF + wr * 64 + m * 16 + fr; PG8_GATHER(ai, m);
;             float sa = 0.f, sb = 0.f;
; #pragma unroll
;             for (int j = 0; j < 8; ++j) { sa += a[j] * a[j]; sb += b[j] * b[j]; }
;             sa += __shfl_xor(sa, 16); sa += __shfl_xor(sa, 32); sb += __shfl_xor(sb, 16); sb += __shfl_xor(sb, 32);
;             if (fq == 0) { P[(rl * 2 + 0) * 4 + wc] = sa; P[(rl * 2 + 1) * 4 + wc] = sb; } }
.LBB0_111:
	s_sub_i32 s3, s36, 20
	s_cmp_gt_u32 s3, -9
	s_mov_b64 s[4:5], -1
	s_cbranch_scc0 .LBB0_161
	v_mul_f32_e32 v133, v125, v125
	v_mul_f32_e32 v135, v117, v117
	v_fmac_f32_e32 v133, v124, v124
	v_fmac_f32_e32 v135, v116, v116
	v_fmac_f32_e32 v133, v126, v126
	v_fmac_f32_e32 v135, v118, v118
	v_and_b32_e32 v130, 64, v184
	v_fmac_f32_e32 v133, v127, v127
	v_fmac_f32_e32 v135, v119, v119
	v_xor_b32_e32 v129, 16, v184
	v_add_u32_e32 v130, 64, v130
	v_fmac_f32_e32 v133, v120, v120
	v_fmac_f32_e32 v135, v112, v112
	v_cmp_lt_i32_e32 vcc, v129, v130
	v_fmac_f32_e32 v133, v121, v121
	v_fmac_f32_e32 v135, v113, v113
	v_cndmask_b32_e32 v129, v184, v129, vcc
	v_fmac_f32_e32 v133, v122, v122
	v_fmac_f32_e32 v135, v114, v114
	v_lshlrev_b32_e32 v129, 2, v129
	v_fmac_f32_e32 v133, v123, v123
	v_fmac_f32_e32 v135, v115, v115
	v_mov_b32_e32 v134, v133
	s_nop 1
	v_permlane16_swap_b32_e32 v134, v133
	v_mov_b32_e32 v144, v135
	s_nop 1
	v_permlane16_swap_b32_e32 v144, v135
	v_xor_b32_e32 v131, 32, v184
	v_cmp_lt_i32_e32 vcc, v131, v130
	v_mov_b32_e32 v128, v176
	s_waitcnt lgkmcnt(0)
	v_add_f32_e32 v133, v133, v134
	v_cndmask_b32_e32 v130, v184, v131, vcc
	v_lshlrev_b32_e32 v132, 2, v130
	v_add_f32_e32 v135, v135, v144
	v_mov_b32_e32 v134, v133
	s_nop 1
	v_permlane32_swap_b32_e32 v134, v133
	v_mov_b32_e32 v144, v135
	s_nop 1
	v_permlane32_swap_b32_e32 v144, v135
	v_mov_b32_e32 v130, v177
	s_nop 0
	v_cmp_eq_u32_e32 vcc, 0, v130
	v_lshl_add_u32 v131, v128, 5, s65
	s_and_saveexec_b64 s[4:5], vcc
	s_cbranch_execz .LBB0_114
	s_waitcnt lgkmcnt(0)
	v_add_f32_e32 v133, v133, v134
	v_add_f32_e32 v134, v135, v144
	ds_write2_b32 v131, v133, v134 offset1:4
.LBB0_114:
	s_or_b64 exec, exec, s[4:5]
	v_mul_f32_e32 v133, v109, v109
	v_mul_f32_e32 v135, v101, v101
	v_fmac_f32_e32 v133, v108, v108
	v_fmac_f32_e32 v135, v100, v100
	v_fmac_f32_e32 v133, v110, v110
	v_fmac_f32_e32 v135, v102, v102
	v_fmac_f32_e32 v133, v111, v111
	v_fmac_f32_e32 v135, v103, v103
	v_fmac_f32_e32 v133, v104, v104
	v_fmac_f32_e32 v135, v96, v96
	v_fmac_f32_e32 v133, v105, v105
	v_fmac_f32_e32 v135, v97, v97
	v_fmac_f32_e32 v133, v106, v106
	v_fmac_f32_e32 v135, v98, v98
	v_fmac_f32_e32 v133, v107, v107
	v_fmac_f32_e32 v135, v99, v99
	s_waitcnt lgkmcnt(0)
	v_mov_b32_e32 v134, v133
	s_nop 1
	v_permlane16_swap_b32_e32 v134, v133
	v_mov_b32_e32 v144, v135
	s_nop 1
	v_permlane16_swap_b32_e32 v144, v135
	s_waitcnt lgkmcnt(0)
	v_add_f32_e32 v133, v133, v134
	v_add_f32_e32 v135, v135, v144
	v_mov_b32_e32 v134, v133
	s_nop 1
	v_permlane32_swap_b32_e32 v134, v133
	v_mov_b32_e32 v144, v135
	s_nop 1
	v_permlane32_swap_b32_e32 v144, v135
	s_and_saveexec_b64 s[4:5], vcc
	s_cbranch_execz .LBB0_116
	s_waitcnt lgkmcnt(0)
	v_add_f32_e32 v133, v133, v134
	v_add_f32_e32 v134, v135, v144
	ds_write2_b32 v131, v133, v134 offset0:128 offset1:132
.LBB0_116:
	s_or_b64 exec, exec, s[4:5]
	v_mul_f32_e32 v133, v93, v93
	v_mul_f32_e32 v135, v85, v85
	v_fmac_f32_e32 v133, v92, v92
	v_fmac_f32_e32 v135, v84, v84
	v_fmac_f32_e32 v133, v94, v94
	v_fmac_f32_e32 v135, v86, v86
	v_fmac_f32_e32 v133, v95, v95
	v_fmac_f32_e32 v135, v87, v87
	v_fmac_f32_e32 v133, v88, v88
	v_fmac_f32_e32 v135, v80, v80
	v_fmac_f32_e32 v133, v89, v89
	v_fmac_f32_e32 v135, v81, v81
	v_fmac_f32_e32 v133, v90, v90
	v_fmac_f32_e32 v135, v82, v82
	v_fmac_f32_e32 v133, v91, v91
	v_fmac_f32_e32 v135, v83, v83
	s_waitcnt lgkmcnt(0)
	v_mov_b32_e32 v134, v133
	s_nop 1
	v_permlane16_swap_b32_e32 v134, v133
	v_mov_b32_e32 v144, v135
	s_nop 1
	v_permlane16_swap_b32_e32 v144, v135
	s_waitcnt lgkmcnt(0)
	v_add_f32_e32 v133, v133, v134
	v_add_f32_e32 v135, v135, v144
	v_mov_b32_e32 v134, v133
	s_nop 1
	v_permlane32_swap_b32_e32 v134, v133
	v_mov_b32_e32 v144, v135
	s_nop 1
	v_permlane32_swap_b32_e32 v144, v135
	s_and_saveexec_b64 s[4:5], vcc
	s_cbranch_execz .LBB0_118
	s_waitcnt lgkmcnt(0)
	v_add_f32_e32 v133, v133, v134
	v_add_f32_e32 v134, v135, v144
	v_add_u32_e32 v135, 0x400, v131
	ds_write2_b32 v135, v133, v134 offset1:4
.LBB0_118:
	s_or_b64 exec, exec, s[4:5]
	v_mul_f32_e32 v133, v77, v77
	v_mul_f32_e32 v135, v69, v69
	v_fmac_f32_e32 v133, v76, v76
	v_fmac_f32_e32 v135, v68, v68
	v_fmac_f32_e32 v133, v78, v78
	v_fmac_f32_e32 v135, v70, v70
	v_fmac_f32_e32 v133, v79, v79
	v_fmac_f32_e32 v135, v71, v71
	v_fmac_f32_e32 v133, v72, v72
	v_fmac_f32_e32 v135, v64, v64
	v_fmac_f32_e32 v133, v73, v73
	v_fmac_f32_e32 v135, v65, v65
	v_fmac_f32_e32 v133, v74, v74
	v_fmac_f32_e32 v135, v66, v66
	v_fmac_f32_e32 v133, v75, v75
	v_fmac_f32_e32 v135, v67, v67
	s_waitcnt lgkmcnt(0)
	v_mov_b32_e32 v134, v133
	s_nop 1
	v_permlane16_swap_b32_e32 v134, v133
	v_mov_b32_e32 v144, v135
	s_nop 1
	v_permlane16_swap_b32_e32 v144, v135
	s_waitcnt lgkmcnt(0)
	v_add_f32_e32 v133, v133, v134
	v_add_f32_e32 v135, v135, v144
	v_mov_b32_e32 v134, v133
	s_nop 1
	v_permlane32_swap_b32_e32 v134, v133
	v_mov_b32_e32 v144, v135
	s_nop 1
	v_permlane32_swap_b32_e32 v144, v135
	s_and_saveexec_b64 s[4:5], vcc
	s_cbranch_execz .LBB0_120
	s_waitcnt lgkmcnt(0)
	v_add_f32_e32 v133, v133, v134
	v_add_f32_e32 v134, v135, v144
	v_add_u32_e32 v135, 0x400, v131
	ds_write2_b32 v135, v133, v134 offset0:128 offset1:132
; #define PG8_GATHER(ai, m) float a[8], b[8]; _Pragma("unroll") for (int j = 0; j < 4; ++j) { a[j] = acc[ai][0][m][0][j]; a[4 + j] = acc[ai][0][m][1][j]; b[j] = acc[ai][1][m][0][j]; b[4 + j] = acc[ai][1][m][1][j]; }
; __device__ __forceinline__ void run_epi_qknorm(const EpiProj& E, const f32x4 (&acc)[2][2][4][2], const Unit& u, int wr, int wc, int fr, int fq, LAS unsigned char* lds) {
;     ...
;         for (int m = 0; m < 4; ++m) { const int rl = ai * HALF + wr * 64 + m * 16 + fr; PG8_GATHER(ai, m);
;             float sa = 0.f, sb = 0.f;
; #pragma unroll
;             for (int j = 0; j < 8; ++j) { sa += a[j] * a[j]; sb += b[j] * b[j]; }
;             sa += __shfl_xor(sa, 16); sa += __shfl_xor(sa, 32); sb += __shfl_xor(sb, 16); sb += __shfl_xor(sb, 32);
;             if (fq == 0) { P[(rl * 2 + 0) * 4 + wc] = sa; P[(rl * 2 + 1) * 4 + wc] = sb; } }
.LBB0_120:
	s_or_b64 exec, exec, s[4:5]
	v_mul_f32_e32 v133, v61, v61
	v_mul_f32_e32 v135, v53, v53
	v_fmac_f32_e32 v133, v60, v60
	v_fmac_f32_e32 v135, v52, v52
	v_fmac_f32_e32 v133, v62, v62
	v_fmac_f32_e32 v135, v54, v54
	v_fmac_f32_e32 v133, v63, v63
	v_fmac_f32_e32 v135, v55, v55
	v_fmac_f32_e32 v133, v56, v56
	v_fmac_f32_e32 v135, v48, v48
	v_fmac_f32_e32 v133, v57, v57
	v_fmac_f32_e32 v135, v49, v49
	v_fmac_f32_e32 v133, v58, v58
	v_fmac_f32_e32 v135, v50, v50
	v_fmac_f32_e32 v133, v59, v59
	v_fmac_f32_e32 v135, v51, v51
	s_waitcnt lgkmcnt(0)
	v_mov_b32_e32 v134, v133
	s_nop 1
	v_permlane16_swap_b32_e32 v134, v133
	v_mov_b32_e32 v144, v135
	s_nop 1
	v_permlane16_swap_b32_e32 v144, v135
	s_waitcnt lgkmcnt(0)
	v_add_f32_e32 v133, v133, v134
	v_add_f32_e32 v135, v135, v144
	v_mov_b32_e32 v134, v133
	s_nop 1
	v_permlane32_swap_b32_e32 v134, v133
	v_mov_b32_e32 v144, v135
	s_nop 1
	v_permlane32_swap_b32_e32 v144, v135
	s_and_saveexec_b64 s[4:5], vcc
	s_cbranch_execz .LBB0_122
	s_waitcnt lgkmcnt(0)
	v_add_f32_e32 v133, v133, v134
	v_add_f32_e32 v134, v135, v144
	v_add_u32_e32 v135, 0x1000, v131
	ds_write2_b32 v135, v133, v134 offset1:4
.LBB0_122:
	s_or_b64 exec, exec, s[4:5]
	v_mul_f32_e32 v133, v45, v45
	v_mul_f32_e32 v135, v37, v37
	v_fmac_f32_e32 v133, v44, v44
	v_fmac_f32_e32 v135, v36, v36
	v_fmac_f32_e32 v133, v46, v46
	v_fmac_f32_e32 v135, v38, v38
	v_fmac_f32_e32 v133, v47, v47
	v_fmac_f32_e32 v135, v39, v39
	v_fmac_f32_e32 v133, v40, v40
	v_fmac_f32_e32 v135, v32, v32
	v_fmac_f32_e32 v133, v41, v41
	v_fmac_f32_e32 v135, v33, v33
	v_fmac_f32_e32 v133, v42, v42
	v_fmac_f32_e32 v135, v34, v34
	v_fmac_f32_e32 v133, v43, v43
	v_fmac_f32_e32 v135, v35, v35
	s_waitcnt lgkmcnt(0)
	v_mov_b32_e32 v134, v133
	s_nop 1
	v_permlane16_swap_b32_e32 v134, v133
	v_mov_b32_e32 v144, v135
	s_nop 1
	v_permlane16_swap_b32_e32 v144, v135
	s_waitcnt lgkmcnt(0)
	v_add_f32_e32 v133, v133, v134
	v_add_f32_e32 v135, v135, v144
	v_mov_b32_e32 v134, v133
	s_nop 1
	v_permlane32_swap_b32_e32 v134, v133
	v_mov_b32_e32 v144, v135
	s_nop 1
	v_permlane32_swap_b32_e32 v144, v135
	s_and_saveexec_b64 s[4:5], vcc
	s_cbranch_execz .LBB0_124
	s_waitcnt lgkmcnt(0)
	v_add_f32_e32 v133, v133, v134
	v_add_f32_e32 v134, v135, v144
	v_add_u32_e32 v135, 0x1000, v131
	ds_write2_b32 v135, v133, v134 offset0:128 offset1:132
.LBB0_124:
	s_or_b64 exec, exec, s[4:5]
	v_mul_f32_e32 v133, v29, v29
	v_mul_f32_e32 v135, v21, v21
	v_fmac_f32_e32 v133, v28, v28
	v_fmac_f32_e32 v135, v20, v20
	v_fmac_f32_e32 v133, v30, v30
	v_fmac_f32_e32 v135, v22, v22
	v_fmac_f32_e32 v133, v31, v31
	v_fmac_f32_e32 v135, v23, v23
	v_fmac_f32_e32 v133, v24, v24
	v_fmac_f32_e32 v135, v16, v16
	v_fmac_f32_e32 v133, v25, v25
	v_fmac_f32_e32 v135, v17, v17
	v_fmac_f32_e32 v133, v26, v26
	v_fmac_f32_e32 v135, v18, v18
	v_fmac_f32_e32 v133, v27, v27
	v_fmac_f32_e32 v135, v19, v19
	s_waitcnt lgkmcnt(0)
	v_mov_b32_e32 v134, v133
	s_nop 1
	v_permlane16_swap_b32_e32 v134, v133
	v_mov_b32_e32 v144, v135
	s_nop 1
	v_permlane16_swap_b32_e32 v144, v135
	s_waitcnt lgkmcnt(0)
	v_add_f32_e32 v133, v133, v134
	v_add_f32_e32 v135, v135, v144
	v_mov_b32_e32 v134, v133
	s_nop 1
	v_permlane32_swap_b32_e32 v134, v133
	v_mov_b32_e32 v144, v135
	s_nop 1
	v_permlane32_swap_b32_e32 v144, v135
	s_and_saveexec_b64 s[4:5], vcc
	s_cbranch_execz .LBB0_126
	s_waitcnt lgkmcnt(0)
	v_add_f32_e32 v133, v133, v134
	v_add_f32_e32 v134, v135, v144
	v_add_u32_e32 v135, 0x1400, v131
	ds_write2_b32 v135, v133, v134 offset1:4
.LBB0_126:
	s_or_b64 exec, exec, s[4:5]
	v_mul_f32_e32 v133, v13, v13
	s_waitcnt lgkmcnt(0)
	v_mul_f32_e32 v134, v5, v5
	v_fmac_f32_e32 v133, v12, v12
	v_fmac_f32_e32 v134, v4, v4
	v_fmac_f32_e32 v133, v14, v14
	v_fmac_f32_e32 v134, v6, v6
	v_fmac_f32_e32 v133, v15, v15
	v_fmac_f32_e32 v134, v7, v7
	v_fmac_f32_e32 v133, v8, v8
	v_fmac_f32_e32 v134, v0, v0
	v_fmac_f32_e32 v133, v9, v9
	v_fmac_f32_e32 v134, v1, v1
	v_fmac_f32_e32 v133, v10, v10
	v_fmac_f32_e32 v134, v2, v2
	v_fmac_f32_e32 v133, v11, v11
	v_fmac_f32_e32 v134, v3, v3
	v_mov_b32_e32 v135, v133
	s_nop 1
	v_permlane16_swap_b32_e32 v135, v133
	v_mov_b32_e32 v144, v134
	s_nop 1
	v_permlane16_swap_b32_e32 v144, v134
	s_waitcnt lgkmcnt(0)
	v_add_f32_e32 v129, v133, v135
	v_add_f32_e32 v134, v134, v144
	v_mov_b32_e32 v133, v129
	s_nop 1
	v_permlane32_swap_b32_e32 v133, v129
	v_mov_b32_e32 v132, v134
	s_nop 1
	v_permlane32_swap_b32_e32 v132, v134
	s_and_saveexec_b64 s[4:5], vcc
	s_cbranch_execz .LBB0_128
	s_waitcnt lgkmcnt(0)
	v_add_f32_e32 v129, v129, v133
	v_add_f32_e32 v132, v134, v132
	v_add_u32_e32 v131, 0x1400, v131
	ds_write2_b32 v131, v129, v132 offset0:128 offset1:132
